# v20: v17 plus nt stores for the in-projection outputs of layers 0-2
# speedup vs baseline: 1.0601x; 1.0016x over previous
.LBB0_284:
	s_lshl_b32 s0, s28, 8
	s_add_i32 s0, s0, s47
	v_add_u32_e32 v170, s0, v162
	v_mov_b32_e32 v164, v170
	v_lshlrev_b64 v[154:155], 2, v[154:155]
	v_ashrrev_i32_e32 v165, 31, v164
	v_lshlrev_b64 v[164:165], 6, v[164:165]
	v_lshl_add_u64 v[164:165], s[10:11], 0, v[164:165]
	v_lshl_add_u64 v[168:169], v[164:165], 0, v[154:155]
	s_waitcnt vmcnt(0)
	v_pk_add_f32 v[166:167], v[128:129], v[132:133]
	v_pk_add_f32 v[164:165], v[126:127], v[130:131]
	global_store_dwordx4 v[168:169], v[164:167], off nt
	s_nop 1
	v_pk_add_f32 v[166:167], v[124:125], v[136:137]
	v_pk_add_f32 v[164:165], v[122:123], v[134:135]
	global_store_dwordx4 v[168:169], v[164:167], off offset:16 nt
	s_nop 1
	v_add_u32_e32 v164, 16, v170
	v_pk_add_f32 v[166:167], v[120:121], v[132:133]
	v_ashrrev_i32_e32 v165, 31, v164
	v_lshlrev_b64 v[164:165], 6, v[164:165]
	v_lshl_add_u64 v[164:165], s[10:11], 0, v[164:165]
	v_lshl_add_u64 v[168:169], v[164:165], 0, v[154:155]
	v_pk_add_f32 v[164:165], v[118:119], v[130:131]
	global_store_dwordx4 v[168:169], v[164:167], off nt
	s_nop 1
	v_pk_add_f32 v[166:167], v[112:113], v[136:137]
	v_pk_add_f32 v[164:165], v[110:111], v[134:135]
	global_store_dwordx4 v[168:169], v[164:167], off offset:16 nt
	s_nop 1
	v_add_u32_e32 v164, 32, v170
	v_pk_add_f32 v[166:167], v[104:105], v[132:133]
	v_ashrrev_i32_e32 v165, 31, v164
	v_lshlrev_b64 v[164:165], 6, v[164:165]
	v_lshl_add_u64 v[164:165], s[10:11], 0, v[164:165]
	v_lshl_add_u64 v[168:169], v[164:165], 0, v[154:155]
	v_pk_add_f32 v[164:165], v[102:103], v[130:131]
	global_store_dwordx4 v[168:169], v[164:167], off nt
	s_nop 1
	v_pk_add_f32 v[166:167], v[96:97], v[136:137]
	v_pk_add_f32 v[164:165], v[94:95], v[134:135]
	global_store_dwordx4 v[168:169], v[164:167], off offset:16 nt
	s_nop 1
	v_add_u32_e32 v164, 48, v170
	v_pk_add_f32 v[166:167], v[88:89], v[132:133]
	v_ashrrev_i32_e32 v165, 31, v164
	v_lshlrev_b64 v[164:165], 6, v[164:165]
	v_lshl_add_u64 v[164:165], s[10:11], 0, v[164:165]
	v_lshl_add_u64 v[168:169], v[164:165], 0, v[154:155]
	v_pk_add_f32 v[164:165], v[86:87], v[130:131]
	global_store_dwordx4 v[168:169], v[164:167], off nt
	s_nop 1
	v_pk_add_f32 v[166:167], v[80:81], v[136:137]
	v_pk_add_f32 v[164:165], v[78:79], v[134:135]
	global_store_dwordx4 v[168:169], v[164:167], off offset:16 nt
	s_nop 1
	v_add_u32_e32 v164, 0x80, v170
	v_pk_add_f32 v[166:167], v[64:65], v[132:133]
	v_ashrrev_i32_e32 v165, 31, v164
	v_lshlrev_b64 v[164:165], 6, v[164:165]
	v_lshl_add_u64 v[164:165], s[10:11], 0, v[164:165]
	v_lshl_add_u64 v[168:169], v[164:165], 0, v[154:155]
	v_pk_add_f32 v[164:165], v[62:63], v[130:131]
	global_store_dwordx4 v[168:169], v[164:167], off nt
	s_nop 1
	v_pk_add_f32 v[166:167], v[60:61], v[136:137]
	v_pk_add_f32 v[164:165], v[58:59], v[134:135]
	global_store_dwordx4 v[168:169], v[164:167], off offset:16 nt
	s_nop 1
	v_add_u32_e32 v164, 0x90, v170
	v_pk_add_f32 v[166:167], v[56:57], v[132:133]
	v_ashrrev_i32_e32 v165, 31, v164
	v_lshlrev_b64 v[164:165], 6, v[164:165]
	v_lshl_add_u64 v[164:165], s[10:11], 0, v[164:165]
	v_lshl_add_u64 v[168:169], v[164:165], 0, v[154:155]
	v_pk_add_f32 v[164:165], v[54:55], v[130:131]
	global_store_dwordx4 v[168:169], v[164:167], off nt
	s_nop 1
	v_pk_add_f32 v[166:167], v[48:49], v[136:137]
	v_pk_add_f32 v[164:165], v[46:47], v[134:135]
	global_store_dwordx4 v[168:169], v[164:167], off offset:16 nt
	s_nop 1
	v_add_u32_e32 v164, 0xa0, v170
	v_pk_add_f32 v[166:167], v[40:41], v[132:133]
	v_ashrrev_i32_e32 v165, 31, v164
	v_lshlrev_b64 v[164:165], 6, v[164:165]
	v_lshl_add_u64 v[164:165], s[10:11], 0, v[164:165]
	v_lshl_add_u64 v[168:169], v[164:165], 0, v[154:155]
	v_pk_add_f32 v[164:165], v[38:39], v[130:131]
	global_store_dwordx4 v[168:169], v[164:167], off nt
	v_pk_add_f32 v[132:133], v[24:25], v[132:133]
	v_pk_add_f32 v[130:131], v[22:23], v[130:131]
	v_pk_add_f32 v[166:167], v[32:33], v[136:137]
	v_pk_add_f32 v[164:165], v[30:31], v[134:135]
	global_store_dwordx4 v[168:169], v[164:167], off offset:16 nt
	s_nop 1
	v_add_u32_e32 v164, 0xb0, v170
	s_nop 0
	v_ashrrev_i32_e32 v165, 31, v164
	v_lshlrev_b64 v[164:165], 6, v[164:165]
	v_lshl_add_u64 v[164:165], s[10:11], 0, v[164:165]
	v_lshl_add_u64 v[154:155], v[164:165], 0, v[154:155]
	global_store_dwordx4 v[154:155], v[130:133], off nt
	s_nop 1
	v_pk_add_f32 v[132:133], v[16:17], v[136:137]
	v_pk_add_f32 v[130:131], v[14:15], v[134:135]
	global_store_dwordx4 v[154:155], v[130:133], off offset:16 nt

.LBB0_286:
	s_andn2_b64 vcc, exec, s[30:31]
	s_cbranch_vccnz .LBB0_274
	s_lshl_b32 s0, s55, 8
	s_or_b32 s0, s0, s48
	s_cmp_lt_i32 s55, 2
	v_lshl_add_u32 v132, v163, 3, s0
	s_cselect_b64 vcc, -1, 0
	s_lshl_b32 s0, s28, 8
	s_add_i32 s0, s0, s47
	v_add_u32_e32 v131, s0, v162
	v_cndmask_b32_e32 v130, 1.0, v161, vcc
	v_ashrrev_i32_e32 v133, 31, v132
	v_mov_b32_e32 v134, v131
	v_lshl_add_u64 v[132:133], v[132:133], 1, s[14:15]
	v_pk_mul_f32 v[128:129], v[130:131], v[128:129] op_sel_hi:[0,1]
	v_pk_mul_f32 v[126:127], v[130:131], v[126:127] op_sel_hi:[0,1]
	v_pk_mul_f32 v[136:137], v[130:131], v[124:125] op_sel_hi:[0,1]
	v_pk_mul_f32 v[124:125], v[130:131], v[122:123] op_sel_hi:[0,1]
	v_mad_i64_i32 v[134:135], s[0:1], v134, s54, v[132:133]
	v_cvt_pk_bf16_f32 v122, v126, v127
	v_cvt_pk_bf16_f32 v123, v128, v129
	v_cvt_pk_bf16_f32 v124, v124, v125
	v_cvt_pk_bf16_f32 v125, v136, v137
	global_store_dwordx4 v[134:135], v[122:125], off nt
	v_pk_mul_f32 v[116:117], v[130:131], v[116:117] op_sel_hi:[0,1]
	v_pk_mul_f32 v[114:115], v[130:131], v[114:115] op_sel_hi:[0,1]
	v_pk_mul_f32 v[122:123], v[130:131], v[108:109] op_sel_hi:[0,1]
	v_pk_mul_f32 v[108:109], v[130:131], v[106:107] op_sel_hi:[0,1]
	v_cvt_pk_bf16_f32 v106, v114, v115
	v_cvt_pk_bf16_f32 v107, v116, v117
	v_cvt_pk_bf16_f32 v108, v108, v109
	v_cvt_pk_bf16_f32 v109, v122, v123
	global_store_dwordx4 v[134:135], v[106:109], off offset:256 nt
	v_pk_mul_f32 v[112:113], v[130:131], v[112:113] op_sel_hi:[0,1]
	v_pk_mul_f32 v[110:111], v[130:131], v[110:111] op_sel_hi:[0,1]
	v_add_u32_e32 v106, 16, v131
	v_pk_mul_f32 v[108:109], v[130:131], v[120:121] op_sel_hi:[0,1]
	v_mad_i64_i32 v[114:115], s[0:1], v106, s54, v[132:133]
	v_pk_mul_f32 v[106:107], v[130:131], v[118:119] op_sel_hi:[0,1]
	v_cvt_pk_bf16_f32 v106, v106, v107
	v_cvt_pk_bf16_f32 v107, v108, v109
	v_cvt_pk_bf16_f32 v108, v110, v111
	v_cvt_pk_bf16_f32 v109, v112, v113
	global_store_dwordx4 v[114:115], v[106:109], off nt
	v_pk_mul_f32 v[100:101], v[130:131], v[100:101] op_sel_hi:[0,1]
	v_pk_mul_f32 v[98:99], v[130:131], v[98:99] op_sel_hi:[0,1]
	v_pk_mul_f32 v[106:107], v[130:131], v[92:93] op_sel_hi:[0,1]
	v_pk_mul_f32 v[92:93], v[130:131], v[90:91] op_sel_hi:[0,1]
	v_cvt_pk_bf16_f32 v90, v98, v99
	v_cvt_pk_bf16_f32 v91, v100, v101
	v_cvt_pk_bf16_f32 v92, v92, v93
	v_cvt_pk_bf16_f32 v93, v106, v107
	global_store_dwordx4 v[114:115], v[90:93], off offset:256 nt
	v_pk_mul_f32 v[96:97], v[130:131], v[96:97] op_sel_hi:[0,1]
	v_pk_mul_f32 v[94:95], v[130:131], v[94:95] op_sel_hi:[0,1]
	v_add_u32_e32 v90, 32, v131
	v_pk_mul_f32 v[92:93], v[130:131], v[104:105] op_sel_hi:[0,1]
	v_mad_i64_i32 v[98:99], s[0:1], v90, s54, v[132:133]
	v_pk_mul_f32 v[90:91], v[130:131], v[102:103] op_sel_hi:[0,1]
	v_cvt_pk_bf16_f32 v90, v90, v91
	v_cvt_pk_bf16_f32 v91, v92, v93
	v_cvt_pk_bf16_f32 v92, v94, v95
	v_cvt_pk_bf16_f32 v93, v96, v97
	global_store_dwordx4 v[98:99], v[90:93], off nt
	v_pk_mul_f32 v[84:85], v[130:131], v[84:85] op_sel_hi:[0,1]
	v_pk_mul_f32 v[82:83], v[130:131], v[82:83] op_sel_hi:[0,1]
	v_pk_mul_f32 v[90:91], v[130:131], v[76:77] op_sel_hi:[0,1]
	v_pk_mul_f32 v[76:77], v[130:131], v[74:75] op_sel_hi:[0,1]
	v_cvt_pk_bf16_f32 v74, v82, v83
	v_cvt_pk_bf16_f32 v75, v84, v85
	v_cvt_pk_bf16_f32 v76, v76, v77
	v_cvt_pk_bf16_f32 v77, v90, v91
	global_store_dwordx4 v[98:99], v[74:77], off offset:256 nt
	v_pk_mul_f32 v[80:81], v[130:131], v[80:81] op_sel_hi:[0,1]
	v_pk_mul_f32 v[78:79], v[130:131], v[78:79] op_sel_hi:[0,1]
	v_add_u32_e32 v74, 48, v131
	v_pk_mul_f32 v[76:77], v[130:131], v[88:89] op_sel_hi:[0,1]
	v_mad_i64_i32 v[82:83], s[0:1], v74, s54, v[132:133]
	v_pk_mul_f32 v[74:75], v[130:131], v[86:87] op_sel_hi:[0,1]
	v_cvt_pk_bf16_f32 v74, v74, v75
	v_cvt_pk_bf16_f32 v75, v76, v77
	v_cvt_pk_bf16_f32 v76, v78, v79
	v_cvt_pk_bf16_f32 v77, v80, v81
	global_store_dwordx4 v[82:83], v[74:77], off nt
	v_pk_mul_f32 v[72:73], v[130:131], v[72:73] op_sel_hi:[0,1]
	v_pk_mul_f32 v[70:71], v[130:131], v[70:71] op_sel_hi:[0,1]
	v_pk_mul_f32 v[74:75], v[130:131], v[68:69] op_sel_hi:[0,1]
	v_pk_mul_f32 v[68:69], v[130:131], v[66:67] op_sel_hi:[0,1]
	v_cvt_pk_bf16_f32 v66, v70, v71
	v_cvt_pk_bf16_f32 v67, v72, v73
	v_cvt_pk_bf16_f32 v68, v68, v69
	v_cvt_pk_bf16_f32 v69, v74, v75
	global_store_dwordx4 v[82:83], v[66:69], off offset:256 nt
	v_pk_mul_f32 v[64:65], v[130:131], v[64:65] op_sel_hi:[0,1]
	v_pk_mul_f32 v[62:63], v[130:131], v[62:63] op_sel_hi:[0,1]
	v_add_u32_e32 v66, 0x80, v131
	v_pk_mul_f32 v[68:69], v[130:131], v[60:61] op_sel_hi:[0,1]
	v_pk_mul_f32 v[60:61], v[130:131], v[58:59] op_sel_hi:[0,1]
	v_mad_i64_i32 v[66:67], s[0:1], v66, s54, v[132:133]
	v_cvt_pk_bf16_f32 v58, v62, v63
	v_cvt_pk_bf16_f32 v59, v64, v65
	v_cvt_pk_bf16_f32 v60, v60, v61
	v_cvt_pk_bf16_f32 v61, v68, v69
	global_store_dwordx4 v[66:67], v[58:61], off nt
	v_pk_mul_f32 v[52:53], v[130:131], v[52:53] op_sel_hi:[0,1]
	v_pk_mul_f32 v[50:51], v[130:131], v[50:51] op_sel_hi:[0,1]
	v_pk_mul_f32 v[58:59], v[130:131], v[44:45] op_sel_hi:[0,1]
	v_pk_mul_f32 v[44:45], v[130:131], v[42:43] op_sel_hi:[0,1]
	v_cvt_pk_bf16_f32 v42, v50, v51
	v_cvt_pk_bf16_f32 v43, v52, v53
	v_cvt_pk_bf16_f32 v44, v44, v45
	v_cvt_pk_bf16_f32 v45, v58, v59
	global_store_dwordx4 v[66:67], v[42:45], off offset:256 nt
	v_pk_mul_f32 v[48:49], v[130:131], v[48:49] op_sel_hi:[0,1]
	v_pk_mul_f32 v[46:47], v[130:131], v[46:47] op_sel_hi:[0,1]
	v_add_u32_e32 v42, 0x90, v131
	v_pk_mul_f32 v[44:45], v[130:131], v[56:57] op_sel_hi:[0,1]
	v_mad_i64_i32 v[50:51], s[0:1], v42, s54, v[132:133]
	v_pk_mul_f32 v[42:43], v[130:131], v[54:55] op_sel_hi:[0,1]
	v_cvt_pk_bf16_f32 v42, v42, v43
	v_cvt_pk_bf16_f32 v43, v44, v45
	v_cvt_pk_bf16_f32 v44, v46, v47
	v_cvt_pk_bf16_f32 v45, v48, v49
	global_store_dwordx4 v[50:51], v[42:45], off nt
	v_pk_mul_f32 v[36:37], v[130:131], v[36:37] op_sel_hi:[0,1]
	v_pk_mul_f32 v[34:35], v[130:131], v[34:35] op_sel_hi:[0,1]
	v_pk_mul_f32 v[42:43], v[130:131], v[28:29] op_sel_hi:[0,1]
	v_pk_mul_f32 v[28:29], v[130:131], v[26:27] op_sel_hi:[0,1]
	v_cvt_pk_bf16_f32 v26, v34, v35
	v_cvt_pk_bf16_f32 v27, v36, v37
	v_cvt_pk_bf16_f32 v28, v28, v29
	v_cvt_pk_bf16_f32 v29, v42, v43
	global_store_dwordx4 v[50:51], v[26:29], off offset:256 nt
	v_pk_mul_f32 v[32:33], v[130:131], v[32:33] op_sel_hi:[0,1]
	v_pk_mul_f32 v[30:31], v[130:131], v[30:31] op_sel_hi:[0,1]
	v_add_u32_e32 v26, 0xa0, v131
	v_pk_mul_f32 v[28:29], v[130:131], v[40:41] op_sel_hi:[0,1]
	v_mad_i64_i32 v[34:35], s[0:1], v26, s54, v[132:133]
	v_pk_mul_f32 v[26:27], v[130:131], v[38:39] op_sel_hi:[0,1]
	v_cvt_pk_bf16_f32 v26, v26, v27
	v_cvt_pk_bf16_f32 v27, v28, v29
	v_cvt_pk_bf16_f32 v28, v30, v31
	v_cvt_pk_bf16_f32 v29, v32, v33
	global_store_dwordx4 v[34:35], v[26:29], off nt
	v_pk_mul_f32 v[20:21], v[130:131], v[20:21] op_sel_hi:[0,1]
	v_pk_mul_f32 v[18:19], v[130:131], v[18:19] op_sel_hi:[0,1]
	v_pk_mul_f32 v[26:27], v[130:131], v[12:13] op_sel_hi:[0,1]
	v_pk_mul_f32 v[12:13], v[130:131], v[10:11] op_sel_hi:[0,1]
	v_cvt_pk_bf16_f32 v10, v18, v19
	v_cvt_pk_bf16_f32 v11, v20, v21
	v_cvt_pk_bf16_f32 v12, v12, v13
	v_cvt_pk_bf16_f32 v13, v26, v27
	global_store_dwordx4 v[34:35], v[10:13], off offset:256 nt
	v_pk_mul_f32 v[16:17], v[130:131], v[16:17] op_sel_hi:[0,1]
	v_pk_mul_f32 v[14:15], v[130:131], v[14:15] op_sel_hi:[0,1]
	v_add_u32_e32 v10, 0xb0, v131
	v_pk_mul_f32 v[12:13], v[130:131], v[24:25] op_sel_hi:[0,1]
	v_mad_i64_i32 v[18:19], s[0:1], v10, s54, v[132:133]
	v_pk_mul_f32 v[10:11], v[130:131], v[22:23] op_sel_hi:[0,1]
	v_cvt_pk_bf16_f32 v10, v10, v11
	v_cvt_pk_bf16_f32 v11, v12, v13
	v_cvt_pk_bf16_f32 v12, v14, v15
	v_cvt_pk_bf16_f32 v13, v16, v17
	global_store_dwordx4 v[18:19], v[10:13], off nt
	v_pk_mul_f32 v[8:9], v[130:131], v[8:9] op_sel_hi:[0,1]
	v_pk_mul_f32 v[6:7], v[130:131], v[6:7] op_sel_hi:[0,1]
	v_pk_mul_f32 v[10:11], v[130:131], v[4:5] op_sel_hi:[0,1]
	v_pk_mul_f32 v[4:5], v[130:131], v[2:3] op_sel_hi:[0,1]
	v_cvt_pk_bf16_f32 v2, v6, v7
	v_cvt_pk_bf16_f32 v3, v8, v9
	v_cvt_pk_bf16_f32 v4, v4, v5
	v_cvt_pk_bf16_f32 v5, v10, v11
	global_store_dwordx4 v[18:19], v[2:5], off offset:256 nt
	s_branch .LBB0_274

.LBB0_895:
	ds_read_b128 v[156:159], v152
	ds_read_b128 v[160:163], v152 offset:1024
	ds_read_b128 v[164:167], v152 offset:2048
	ds_read_b128 v[168:171], v152 offset:3072
	s_add_u32 s0, s30, 0xfffc0080
	s_addc_u32 s1, s31, -1
	s_cmp_eq_u32 s55, 12
	s_cselect_b32 s37, s23, s1
	s_cselect_b32 s36, s51, s0
	s_cselect_b32 s35, s21, s54
	s_cselect_b32 s34, s52, s53
	v_lshl_add_u64 v[148:149], s[30:31], 0, v[140:141]
	s_add_i32 m0, s25, 0xc000
	ds_read_b128 v[172:175], v153
	ds_read_b128 v[176:179], v153 offset:1024
	ds_read_b128 v[180:183], v153 offset:2048
	ds_read_b128 v[184:187], v153 offset:3072
	ds_read_b128 v[188:191], v153 offset:4096
	ds_read_b128 v[192:195], v153 offset:5120
	ds_read_b128 v[196:199], v153 offset:6144
	ds_read_b128 v[200:203], v153 offset:7168
	global_load_lds_dwordx4 v[148:149], off
	v_lshl_add_u64 v[148:149], s[30:31], 0, v[138:139]
	s_add_i32 m0, s25, 0xe000
	s_nop 0
	global_load_lds_dwordx4 v[148:149], off
	s_waitcnt lgkmcnt(8)
	s_waitcnt vmcnt(10)
	s_barrier
	s_waitcnt lgkmcnt(0)
	s_waitcnt lgkmcnt(0)
	v_mfma_f32_16x16x32_bf16 v[126:129], v[156:159], v[172:175], v[126:129]
	v_mfma_f32_16x16x32_bf16 v[122:125], v[164:167], v[172:175], v[122:125]
	v_mfma_f32_16x16x32_bf16 v[118:121], v[156:159], v[180:183], v[118:121]
	v_mfma_f32_16x16x32_bf16 v[110:113], v[164:167], v[180:183], v[110:113]
	v_mfma_f32_16x16x32_bf16 v[102:105], v[156:159], v[188:191], v[102:105]
	v_mfma_f32_16x16x32_bf16 v[94:97], v[164:167], v[188:191], v[94:97]
	v_mfma_f32_16x16x32_bf16 v[86:89], v[156:159], v[196:199], v[86:89]
	v_mfma_f32_16x16x32_bf16 v[78:81], v[164:167], v[196:199], v[78:81]
	v_mfma_f32_16x16x32_bf16 v[126:129], v[160:163], v[176:179], v[126:129]
	v_mfma_f32_16x16x32_bf16 v[122:125], v[168:171], v[176:179], v[122:125]
	v_mfma_f32_16x16x32_bf16 v[118:121], v[160:163], v[184:187], v[118:121]
	v_mfma_f32_16x16x32_bf16 v[110:113], v[168:171], v[184:187], v[110:113]
	v_mfma_f32_16x16x32_bf16 v[102:105], v[160:163], v[192:195], v[102:105]
	v_mfma_f32_16x16x32_bf16 v[94:97], v[168:171], v[192:195], v[94:97]
	v_mfma_f32_16x16x32_bf16 v[86:89], v[160:163], v[200:203], v[86:89]
	v_mfma_f32_16x16x32_bf16 v[78:81], v[168:171], v[200:203], v[78:81]
	s_barrier
	s_add_i32 s0, s47, s11
	v_lshl_add_u64 v[148:149], s[34:35], 0, v[134:135]
	s_mov_b32 m0, s0
	ds_read_b128 v[204:207], v154
	ds_read_b128 v[208:211], v154 offset:1024
	ds_read_b128 v[212:215], v154 offset:2048
	ds_read_b128 v[216:219], v154 offset:3072
	global_load_lds_dwordx4 v[148:149], off
	v_lshl_add_u64 v[220:221], s[34:35], 0, v[130:131]
	s_add_i32 m0, s0, 0x2000
	s_nop 0
	global_load_lds_dwordx4 v[220:221], off
	s_waitcnt vmcnt(10)
	s_barrier
	s_waitcnt lgkmcnt(0)
	s_waitcnt lgkmcnt(0)
	v_mfma_f32_16x16x32_bf16 v[114:117], v[204:207], v[172:175], v[114:117]
	v_mfma_f32_16x16x32_bf16 v[106:109], v[212:215], v[172:175], v[106:109]
	v_mfma_f32_16x16x32_bf16 v[98:101], v[204:207], v[180:183], v[98:101]
	v_mfma_f32_16x16x32_bf16 v[90:93], v[212:215], v[180:183], v[90:93]
	v_mfma_f32_16x16x32_bf16 v[82:85], v[204:207], v[188:191], v[82:85]
	v_mfma_f32_16x16x32_bf16 v[74:77], v[212:215], v[188:191], v[74:77]
	v_mfma_f32_16x16x32_bf16 v[70:73], v[204:207], v[196:199], v[70:73]
	v_mfma_f32_16x16x32_bf16 v[66:69], v[212:215], v[196:199], v[66:69]
	v_mfma_f32_16x16x32_bf16 v[114:117], v[208:211], v[176:179], v[114:117]
	v_mfma_f32_16x16x32_bf16 v[106:109], v[216:219], v[176:179], v[106:109]
	v_mfma_f32_16x16x32_bf16 v[98:101], v[208:211], v[184:187], v[98:101]
	v_mfma_f32_16x16x32_bf16 v[90:93], v[216:219], v[184:187], v[90:93]
	v_mfma_f32_16x16x32_bf16 v[82:85], v[208:211], v[192:195], v[82:85]
	v_mfma_f32_16x16x32_bf16 v[74:77], v[216:219], v[192:195], v[74:77]
	v_mfma_f32_16x16x32_bf16 v[70:73], v[208:211], v[200:203], v[70:73]
	v_mfma_f32_16x16x32_bf16 v[66:69], v[216:219], v[200:203], v[66:69]
	s_mov_b32 m0, s25
	v_lshl_add_u64 v[222:223], s[36:37], 0, v[136:137]
	s_barrier
	ds_read_b128 v[172:175], v153 offset:16384
	ds_read_b128 v[176:179], v153 offset:17408
	ds_read_b128 v[180:183], v153 offset:18432
	ds_read_b128 v[184:187], v153 offset:19456
	ds_read_b128 v[188:191], v153 offset:20480
	ds_read_b128 v[192:195], v153 offset:21504
	ds_read_b128 v[196:199], v153 offset:22528
	ds_read_b128 v[200:203], v153 offset:23552
	global_load_lds_dwordx4 v[222:223], off
	v_lshl_add_u64 v[224:225], s[36:37], 0, v[132:133]
	s_mov_b32 m0, s39
	s_nop 0
	global_load_lds_dwordx4 v[224:225], off
	s_waitcnt vmcnt(10)
	s_barrier
	s_waitcnt lgkmcnt(0)
	s_waitcnt lgkmcnt(0)
	v_mfma_f32_16x16x32_bf16 v[62:65], v[156:159], v[172:175], v[62:65]
	v_mfma_f32_16x16x32_bf16 v[58:61], v[164:167], v[172:175], v[58:61]
	v_mfma_f32_16x16x32_bf16 v[54:57], v[156:159], v[180:183], v[54:57]
	v_mfma_f32_16x16x32_bf16 v[46:49], v[164:167], v[180:183], v[46:49]
	v_mfma_f32_16x16x32_bf16 v[38:41], v[156:159], v[188:191], v[38:41]
	v_mfma_f32_16x16x32_bf16 v[30:33], v[164:167], v[188:191], v[30:33]
	v_mfma_f32_16x16x32_bf16 v[22:25], v[156:159], v[196:199], v[22:25]
	v_mfma_f32_16x16x32_bf16 v[14:17], v[164:167], v[196:199], v[14:17]
	v_mfma_f32_16x16x32_bf16 v[62:65], v[160:163], v[176:179], v[62:65]
	v_mfma_f32_16x16x32_bf16 v[58:61], v[168:171], v[176:179], v[58:61]
	v_mfma_f32_16x16x32_bf16 v[54:57], v[160:163], v[184:187], v[54:57]
	v_mfma_f32_16x16x32_bf16 v[46:49], v[168:171], v[184:187], v[46:49]
	v_mfma_f32_16x16x32_bf16 v[38:41], v[160:163], v[192:195], v[38:41]
	v_mfma_f32_16x16x32_bf16 v[30:33], v[168:171], v[192:195], v[30:33]
	v_mfma_f32_16x16x32_bf16 v[22:25], v[160:163], v[200:203], v[22:25]
	v_mfma_f32_16x16x32_bf16 v[14:17], v[168:171], v[200:203], v[14:17]
	s_barrier
	s_add_u32 s0, s34, 0x40000
	s_addc_u32 s1, s35, 0
	s_add_i32 s56, s48, s11
	v_lshl_add_u64 v[156:157], s[0:1], 0, v[134:135]
	s_mov_b32 m0, s56
	s_nop 0
	global_load_lds_dwordx4 v[156:157], off
	v_lshl_add_u64 v[156:157], s[0:1], 0, v[130:131]
	s_add_i32 m0, s56, 0x2000
	s_nop 0
	global_load_lds_dwordx4 v[156:157], off
	s_waitcnt vmcnt(10)
	s_barrier
	v_mfma_f32_16x16x32_bf16 v[50:53], v[204:207], v[172:175], v[50:53]
	v_mfma_f32_16x16x32_bf16 v[42:45], v[212:215], v[172:175], v[42:45]
	v_mfma_f32_16x16x32_bf16 v[34:37], v[204:207], v[180:183], v[34:37]
	v_mfma_f32_16x16x32_bf16 v[26:29], v[212:215], v[180:183], v[26:29]
	v_mfma_f32_16x16x32_bf16 v[18:21], v[204:207], v[188:191], v[18:21]
	v_mfma_f32_16x16x32_bf16 v[10:13], v[212:215], v[188:191], v[10:13]
	v_mfma_f32_16x16x32_bf16 v[6:9], v[204:207], v[196:199], v[6:9]
	v_mfma_f32_16x16x32_bf16 v[2:5], v[212:215], v[196:199], v[2:5]
	v_mfma_f32_16x16x32_bf16 v[50:53], v[208:211], v[176:179], v[50:53]
	v_mfma_f32_16x16x32_bf16 v[42:45], v[216:219], v[176:179], v[42:45]
	v_mfma_f32_16x16x32_bf16 v[34:37], v[208:211], v[184:187], v[34:37]
	v_mfma_f32_16x16x32_bf16 v[26:29], v[216:219], v[184:187], v[26:29]
	v_mfma_f32_16x16x32_bf16 v[18:21], v[208:211], v[192:195], v[18:21]
	v_mfma_f32_16x16x32_bf16 v[10:13], v[216:219], v[192:195], v[10:13]
	v_mfma_f32_16x16x32_bf16 v[6:9], v[208:211], v[200:203], v[6:9]
	v_mfma_f32_16x16x32_bf16 v[2:5], v[216:219], v[200:203], v[2:5]
	s_add_i32 s56, 0, 0x18000
	v_add_u32_e32 v146, s56, v151
	s_barrier
	ds_read_b128 v[156:159], v146
	ds_read_b128 v[160:163], v146 offset:1024
	ds_read_b128 v[164:167], v146 offset:2048
	ds_read_b128 v[168:171], v146 offset:3072
	s_add_u32 s0, s36, 0x40000
	s_addc_u32 s1, s37, 0
	s_mov_b32 m0, s40
	v_lshl_add_u64 v[204:205], s[0:1], 0, v[136:137]
	ds_read_b128 v[172:175], v153 offset:32768
	ds_read_b128 v[176:179], v153 offset:33792
	ds_read_b128 v[180:183], v153 offset:34816
	ds_read_b128 v[184:187], v153 offset:35840
	ds_read_b128 v[188:191], v153 offset:36864
	ds_read_b128 v[192:195], v153 offset:37888
	ds_read_b128 v[196:199], v153 offset:38912
	ds_read_b128 v[200:203], v153 offset:39936
	global_load_lds_dwordx4 v[204:205], off
	v_lshl_add_u64 v[204:205], s[0:1], 0, v[132:133]
	s_mov_b32 m0, s41
	s_nop 0
	global_load_lds_dwordx4 v[204:205], off
	s_waitcnt lgkmcnt(8)
	s_waitcnt vmcnt(10)
	s_barrier
	s_waitcnt lgkmcnt(0)
	s_waitcnt lgkmcnt(0)
	v_mfma_f32_16x16x32_bf16 v[126:129], v[156:159], v[172:175], v[126:129]
	v_mfma_f32_16x16x32_bf16 v[122:125], v[164:167], v[172:175], v[122:125]
	v_mfma_f32_16x16x32_bf16 v[118:121], v[156:159], v[180:183], v[118:121]
	v_mfma_f32_16x16x32_bf16 v[110:113], v[164:167], v[180:183], v[110:113]
	v_mfma_f32_16x16x32_bf16 v[102:105], v[156:159], v[188:191], v[102:105]
	v_mfma_f32_16x16x32_bf16 v[94:97], v[164:167], v[188:191], v[94:97]
	v_mfma_f32_16x16x32_bf16 v[86:89], v[156:159], v[196:199], v[86:89]
	v_mfma_f32_16x16x32_bf16 v[78:81], v[164:167], v[196:199], v[78:81]
	v_mfma_f32_16x16x32_bf16 v[126:129], v[160:163], v[176:179], v[126:129]
	v_mfma_f32_16x16x32_bf16 v[122:125], v[168:171], v[176:179], v[122:125]
	v_mfma_f32_16x16x32_bf16 v[118:121], v[160:163], v[184:187], v[118:121]
	v_mfma_f32_16x16x32_bf16 v[110:113], v[168:171], v[184:187], v[110:113]
	v_mfma_f32_16x16x32_bf16 v[102:105], v[160:163], v[192:195], v[102:105]
	v_mfma_f32_16x16x32_bf16 v[94:97], v[168:171], v[192:195], v[94:97]
	v_mfma_f32_16x16x32_bf16 v[86:89], v[160:163], v[200:203], v[86:89]
	v_mfma_f32_16x16x32_bf16 v[78:81], v[168:171], v[200:203], v[78:81]
	s_barrier
	s_add_i32 s36, 0, 0x1c000
	s_add_i32 s0, s56, s11
	v_add_u32_e32 v146, s36, v151
	v_lshl_add_u64 v[148:149], v[148:149], 0, s[16:17]
	s_mov_b32 m0, s0
	ds_read_b128 v[204:207], v146
	ds_read_b128 v[208:211], v146 offset:1024
	ds_read_b128 v[212:215], v146 offset:2048
	ds_read_b128 v[216:219], v146 offset:3072
	global_load_lds_dwordx4 v[148:149], off
	v_lshl_add_u64 v[148:149], v[220:221], 0, s[16:17]
	s_add_i32 m0, s0, 0x2000
	s_nop 0
	global_load_lds_dwordx4 v[148:149], off
	s_waitcnt vmcnt(10)
	s_barrier
	s_waitcnt lgkmcnt(0)
	s_waitcnt lgkmcnt(0)
	v_mfma_f32_16x16x32_bf16 v[114:117], v[204:207], v[172:175], v[114:117]
	v_mfma_f32_16x16x32_bf16 v[106:109], v[212:215], v[172:175], v[106:109]
	v_mfma_f32_16x16x32_bf16 v[98:101], v[204:207], v[180:183], v[98:101]
	v_mfma_f32_16x16x32_bf16 v[90:93], v[212:215], v[180:183], v[90:93]
	v_mfma_f32_16x16x32_bf16 v[82:85], v[204:207], v[188:191], v[82:85]
	v_mfma_f32_16x16x32_bf16 v[74:77], v[212:215], v[188:191], v[74:77]
	v_mfma_f32_16x16x32_bf16 v[70:73], v[204:207], v[196:199], v[70:73]
	v_mfma_f32_16x16x32_bf16 v[66:69], v[212:215], v[196:199], v[66:69]
	v_mfma_f32_16x16x32_bf16 v[114:117], v[208:211], v[176:179], v[114:117]
	v_mfma_f32_16x16x32_bf16 v[106:109], v[216:219], v[176:179], v[106:109]
	v_mfma_f32_16x16x32_bf16 v[98:101], v[208:211], v[184:187], v[98:101]
	v_mfma_f32_16x16x32_bf16 v[90:93], v[216:219], v[184:187], v[90:93]
	v_mfma_f32_16x16x32_bf16 v[82:85], v[208:211], v[192:195], v[82:85]
	v_mfma_f32_16x16x32_bf16 v[74:77], v[216:219], v[192:195], v[74:77]
	v_mfma_f32_16x16x32_bf16 v[70:73], v[208:211], v[200:203], v[70:73]
	v_mfma_f32_16x16x32_bf16 v[66:69], v[216:219], v[200:203], v[66:69]
	s_mov_b32 m0, s45
	v_lshl_add_u64 v[148:149], v[222:223], 0, s[16:17]
	s_barrier
	ds_read_b128 v[172:175], v153 offset:49152
	ds_read_b128 v[176:179], v153 offset:50176
	ds_read_b128 v[180:183], v153 offset:51200
	ds_read_b128 v[184:187], v153 offset:52224
	ds_read_b128 v[188:191], v153 offset:53248
	ds_read_b128 v[192:195], v153 offset:54272
	ds_read_b128 v[196:199], v153 offset:55296
	ds_read_b128 v[200:203], v153 offset:56320
	global_load_lds_dwordx4 v[148:149], off
	v_lshl_add_u64 v[148:149], v[224:225], 0, s[16:17]
	s_mov_b32 m0, s46
	s_nop 0
	global_load_lds_dwordx4 v[148:149], off
	s_waitcnt vmcnt(10)
	s_barrier
	s_waitcnt lgkmcnt(0)
	s_waitcnt lgkmcnt(0)
	v_mfma_f32_16x16x32_bf16 v[62:65], v[156:159], v[172:175], v[62:65]
	v_mfma_f32_16x16x32_bf16 v[58:61], v[164:167], v[172:175], v[58:61]
	v_mfma_f32_16x16x32_bf16 v[54:57], v[156:159], v[180:183], v[54:57]
	v_mfma_f32_16x16x32_bf16 v[46:49], v[164:167], v[180:183], v[46:49]
	v_mfma_f32_16x16x32_bf16 v[38:41], v[156:159], v[188:191], v[38:41]
	v_mfma_f32_16x16x32_bf16 v[30:33], v[164:167], v[188:191], v[30:33]
	v_mfma_f32_16x16x32_bf16 v[22:25], v[156:159], v[196:199], v[22:25]
	v_mfma_f32_16x16x32_bf16 v[14:17], v[164:167], v[196:199], v[14:17]
	v_mfma_f32_16x16x32_bf16 v[62:65], v[160:163], v[176:179], v[62:65]
	v_mfma_f32_16x16x32_bf16 v[58:61], v[168:171], v[176:179], v[58:61]
	v_mfma_f32_16x16x32_bf16 v[54:57], v[160:163], v[184:187], v[54:57]
	v_mfma_f32_16x16x32_bf16 v[46:49], v[168:171], v[184:187], v[46:49]
	v_mfma_f32_16x16x32_bf16 v[38:41], v[160:163], v[192:195], v[38:41]
	v_mfma_f32_16x16x32_bf16 v[30:33], v[168:171], v[192:195], v[30:33]
	v_mfma_f32_16x16x32_bf16 v[22:25], v[160:163], v[200:203], v[22:25]
	v_mfma_f32_16x16x32_bf16 v[14:17], v[168:171], v[200:203], v[14:17]
	s_barrier
	s_add_u32 s0, s34, 0x40080
	s_addc_u32 s1, s35, 0
	s_add_i32 s34, s36, s11
	v_lshl_add_u64 v[148:149], s[0:1], 0, v[134:135]
	s_mov_b32 m0, s34
	s_nop 0
	global_load_lds_dwordx4 v[148:149], off
	v_lshl_add_u64 v[148:149], s[0:1], 0, v[130:131]
	s_add_i32 m0, s34, 0x2000
	s_nop 0
	global_load_lds_dwordx4 v[148:149], off
	s_waitcnt vmcnt(10)
	s_barrier
	v_mfma_f32_16x16x32_bf16 v[50:53], v[204:207], v[172:175], v[50:53]
	v_mfma_f32_16x16x32_bf16 v[42:45], v[212:215], v[172:175], v[42:45]
	v_mfma_f32_16x16x32_bf16 v[34:37], v[204:207], v[180:183], v[34:37]
	v_mfma_f32_16x16x32_bf16 v[26:29], v[212:215], v[180:183], v[26:29]
	v_mfma_f32_16x16x32_bf16 v[18:21], v[204:207], v[188:191], v[18:21]
	v_mfma_f32_16x16x32_bf16 v[10:13], v[212:215], v[188:191], v[10:13]
	v_mfma_f32_16x16x32_bf16 v[6:9], v[204:207], v[196:199], v[6:9]
	v_mfma_f32_16x16x32_bf16 v[2:5], v[212:215], v[196:199], v[2:5]
	v_mfma_f32_16x16x32_bf16 v[50:53], v[208:211], v[176:179], v[50:53]
	v_mfma_f32_16x16x32_bf16 v[42:45], v[216:219], v[176:179], v[42:45]
	v_mfma_f32_16x16x32_bf16 v[34:37], v[208:211], v[184:187], v[34:37]
	v_mfma_f32_16x16x32_bf16 v[26:29], v[216:219], v[184:187], v[26:29]
	v_mfma_f32_16x16x32_bf16 v[18:21], v[208:211], v[192:195], v[18:21]
	v_mfma_f32_16x16x32_bf16 v[10:13], v[216:219], v[192:195], v[10:13]
	v_mfma_f32_16x16x32_bf16 v[6:9], v[208:211], v[200:203], v[6:9]
	v_mfma_f32_16x16x32_bf16 v[2:5], v[216:219], v[200:203], v[2:5]
	s_add_i32 s55, s55, 2
	s_add_u32 s53, s53, 0x100
	s_addc_u32 s54, s54, 0
	s_add_u32 s30, s30, 0x100
	s_addc_u32 s31, s31, 0
	s_cmp_gt_u32 s55, 13
	s_barrier
	s_cbranch_scc0 .LBB0_895
	v_mov_b32_e32 v156, v147
	v_mov_b32_e32 v146, v150
	s_cmp_gt_i32 s50, 11
	s_mov_b64 s[30:31], -1
	s_cbranch_scc0 .LBB0_900
	s_cmp_eq_u32 s50, 12
	s_cselect_b64 s[0:1], -1, 0
	s_and_b64 s[0:1], s[0:1], s[18:19]
	v_cmp_gt_i32_e32 vcc, 4, v146
	s_and_b64 s[0:1], s[0:1], vcc
	s_and_saveexec_b64 s[30:31], s[0:1]
	s_cbranch_execz .LBB0_899
	s_lshl_b32 s0, s24, 8
	s_add_i32 s0, s0, s43
	v_add_u32_e32 v157, s0, v156
	v_mov_b32_e32 v158, v157
	v_lshlrev_b32_e32 v148, 3, v146
	v_ashrrev_i32_e32 v149, 31, v148
	v_ashrrev_i32_e32 v159, 31, v158
	v_lshlrev_b64 v[158:159], 7, v[158:159]
	v_lshl_add_u64 v[158:159], s[14:15], 0, v[158:159]
	v_lshlrev_b64 v[148:149], 2, v[148:149]
	v_lshl_add_u64 v[162:163], v[158:159], 0, v[148:149]
	v_pk_add_f32 v[160:161], v[128:129], 0 op_sel_hi:[1,0]
	v_pk_add_f32 v[158:159], v[126:127], 0 op_sel_hi:[1,0]
	global_store_dwordx4 v[162:163], v[158:161], off nt
	s_nop 1
	v_pk_add_f32 v[160:161], v[124:125], 0 op_sel_hi:[1,0]
	v_pk_add_f32 v[158:159], v[122:123], 0 op_sel_hi:[1,0]
	global_store_dwordx4 v[162:163], v[158:161], off offset:16 nt
	s_nop 1
	v_add_u32_e32 v158, 16, v157
	v_pk_add_f32 v[160:161], v[120:121], 0 op_sel_hi:[1,0]
	v_ashrrev_i32_e32 v159, 31, v158
	v_lshlrev_b64 v[158:159], 7, v[158:159]
	v_lshl_add_u64 v[158:159], s[14:15], 0, v[158:159]
	v_lshl_add_u64 v[162:163], v[158:159], 0, v[148:149]
	v_pk_add_f32 v[158:159], v[118:119], 0 op_sel_hi:[1,0]
	global_store_dwordx4 v[162:163], v[158:161], off nt
	s_nop 1
	v_pk_add_f32 v[160:161], v[112:113], 0 op_sel_hi:[1,0]
	v_pk_add_f32 v[158:159], v[110:111], 0 op_sel_hi:[1,0]
	global_store_dwordx4 v[162:163], v[158:161], off offset:16 nt
	s_nop 1
	v_add_u32_e32 v158, 32, v157
	v_pk_add_f32 v[160:161], v[104:105], 0 op_sel_hi:[1,0]
	v_ashrrev_i32_e32 v159, 31, v158
	v_lshlrev_b64 v[158:159], 7, v[158:159]
	v_lshl_add_u64 v[158:159], s[14:15], 0, v[158:159]
	v_lshl_add_u64 v[162:163], v[158:159], 0, v[148:149]
	v_pk_add_f32 v[158:159], v[102:103], 0 op_sel_hi:[1,0]
	global_store_dwordx4 v[162:163], v[158:161], off nt
	s_nop 1
	v_pk_add_f32 v[160:161], v[96:97], 0 op_sel_hi:[1,0]
	v_pk_add_f32 v[158:159], v[94:95], 0 op_sel_hi:[1,0]
	global_store_dwordx4 v[162:163], v[158:161], off offset:16 nt
	s_nop 1
	v_add_u32_e32 v158, 48, v157
	v_pk_add_f32 v[160:161], v[88:89], 0 op_sel_hi:[1,0]
	v_ashrrev_i32_e32 v159, 31, v158
	v_lshlrev_b64 v[158:159], 7, v[158:159]
	v_lshl_add_u64 v[158:159], s[14:15], 0, v[158:159]
	v_lshl_add_u64 v[162:163], v[158:159], 0, v[148:149]
	v_pk_add_f32 v[158:159], v[86:87], 0 op_sel_hi:[1,0]
	global_store_dwordx4 v[162:163], v[158:161], off nt
	s_nop 1
	v_pk_add_f32 v[160:161], v[80:81], 0 op_sel_hi:[1,0]
	v_pk_add_f32 v[158:159], v[78:79], 0 op_sel_hi:[1,0]
	global_store_dwordx4 v[162:163], v[158:161], off offset:16 nt
	s_nop 1
	v_add_u32_e32 v158, 0x80, v157
	v_pk_add_f32 v[160:161], v[64:65], 0 op_sel_hi:[1,0]
	v_ashrrev_i32_e32 v159, 31, v158
	v_lshlrev_b64 v[158:159], 7, v[158:159]
	v_lshl_add_u64 v[158:159], s[14:15], 0, v[158:159]
	v_lshl_add_u64 v[162:163], v[158:159], 0, v[148:149]
	v_pk_add_f32 v[158:159], v[62:63], 0 op_sel_hi:[1,0]
	global_store_dwordx4 v[162:163], v[158:161], off nt
	s_nop 1
	v_pk_add_f32 v[160:161], v[60:61], 0 op_sel_hi:[1,0]
	v_pk_add_f32 v[158:159], v[58:59], 0 op_sel_hi:[1,0]
	global_store_dwordx4 v[162:163], v[158:161], off offset:16 nt
	s_nop 1
	v_add_u32_e32 v158, 0x90, v157
	v_pk_add_f32 v[160:161], v[56:57], 0 op_sel_hi:[1,0]
	v_ashrrev_i32_e32 v159, 31, v158
	v_lshlrev_b64 v[158:159], 7, v[158:159]
	v_lshl_add_u64 v[158:159], s[14:15], 0, v[158:159]
	v_lshl_add_u64 v[162:163], v[158:159], 0, v[148:149]
	v_pk_add_f32 v[158:159], v[54:55], 0 op_sel_hi:[1,0]
	global_store_dwordx4 v[162:163], v[158:161], off nt
	s_nop 1
	v_pk_add_f32 v[160:161], v[48:49], 0 op_sel_hi:[1,0]
	v_pk_add_f32 v[158:159], v[46:47], 0 op_sel_hi:[1,0]
	global_store_dwordx4 v[162:163], v[158:161], off offset:16 nt
	s_nop 1
	v_add_u32_e32 v158, 0xa0, v157
	v_pk_add_f32 v[160:161], v[40:41], 0 op_sel_hi:[1,0]
	v_ashrrev_i32_e32 v159, 31, v158
	v_lshlrev_b64 v[158:159], 7, v[158:159]
	v_lshl_add_u64 v[158:159], s[14:15], 0, v[158:159]
	v_lshl_add_u64 v[162:163], v[158:159], 0, v[148:149]
	v_pk_add_f32 v[158:159], v[38:39], 0 op_sel_hi:[1,0]
	global_store_dwordx4 v[162:163], v[158:161], off nt
	s_nop 1
	v_pk_add_f32 v[160:161], v[32:33], 0 op_sel_hi:[1,0]
	v_pk_add_f32 v[158:159], v[30:31], 0 op_sel_hi:[1,0]
	global_store_dwordx4 v[162:163], v[158:161], off offset:16 nt
	s_nop 1
	v_add_u32_e32 v158, 0xb0, v157
	v_pk_add_f32 v[160:161], v[24:25], 0 op_sel_hi:[1,0]
	v_ashrrev_i32_e32 v159, 31, v158
	v_lshlrev_b64 v[158:159], 7, v[158:159]
	v_lshl_add_u64 v[158:159], s[14:15], 0, v[158:159]
	v_lshl_add_u64 v[148:149], v[158:159], 0, v[148:149]
	v_pk_add_f32 v[158:159], v[22:23], 0 op_sel_hi:[1,0]
	global_store_dwordx4 v[148:149], v[158:161], off nt
	s_nop 1
	v_pk_add_f32 v[160:161], v[16:17], 0 op_sel_hi:[1,0]
	v_pk_add_f32 v[158:159], v[14:15], 0 op_sel_hi:[1,0]
	global_store_dwordx4 v[148:149], v[158:161], off offset:16 nt

.LBB0_900:
	s_andn2_b64 vcc, exec, s[30:31]
	s_cbranch_vccnz .LBB0_891
	s_lshl_b32 s0, s50, 8
	s_or_b32 s0, s0, s44
	s_cmp_lt_i32 s50, 2
	v_lshl_add_u32 v148, v146, 3, s0
	s_cselect_b64 vcc, -1, 0
	s_lshl_b32 s0, s24, 8
	s_add_i32 s0, s0, s43
	v_add_u32_e32 v160, s0, v156
	v_cndmask_b32_e32 v146, 1.0, v155, vcc
	v_ashrrev_i32_e32 v149, 31, v148
	v_mov_b32_e32 v156, v160
	v_lshl_add_u64 v[148:149], v[148:149], 1, s[12:13]
	v_pk_mul_f32 v[128:129], v[146:147], v[128:129] op_sel_hi:[0,1]
	v_pk_mul_f32 v[126:127], v[146:147], v[126:127] op_sel_hi:[0,1]
	v_pk_mul_f32 v[158:159], v[146:147], v[124:125] op_sel_hi:[0,1]
	v_pk_mul_f32 v[124:125], v[146:147], v[122:123] op_sel_hi:[0,1]
	v_mad_i64_i32 v[156:157], s[0:1], v156, s49, v[148:149]
	v_cvt_pk_bf16_f32 v122, v126, v127
	v_cvt_pk_bf16_f32 v123, v128, v129
	v_cvt_pk_bf16_f32 v124, v124, v125
	v_cvt_pk_bf16_f32 v125, v158, v159
	global_store_dwordx4 v[156:157], v[122:125], off nt
	v_pk_mul_f32 v[116:117], v[146:147], v[116:117] op_sel_hi:[0,1]
	v_pk_mul_f32 v[114:115], v[146:147], v[114:115] op_sel_hi:[0,1]
	v_pk_mul_f32 v[122:123], v[146:147], v[108:109] op_sel_hi:[0,1]
	v_pk_mul_f32 v[108:109], v[146:147], v[106:107] op_sel_hi:[0,1]
	v_cvt_pk_bf16_f32 v106, v114, v115
	v_cvt_pk_bf16_f32 v107, v116, v117
	v_cvt_pk_bf16_f32 v108, v108, v109
	v_cvt_pk_bf16_f32 v109, v122, v123
	global_store_dwordx4 v[156:157], v[106:109], off offset:256 nt
	v_pk_mul_f32 v[112:113], v[146:147], v[112:113] op_sel_hi:[0,1]
	v_pk_mul_f32 v[110:111], v[146:147], v[110:111] op_sel_hi:[0,1]
	v_add_u32_e32 v106, 16, v160
	v_pk_mul_f32 v[108:109], v[146:147], v[120:121] op_sel_hi:[0,1]
	v_mad_i64_i32 v[114:115], s[0:1], v106, s49, v[148:149]
	v_pk_mul_f32 v[106:107], v[146:147], v[118:119] op_sel_hi:[0,1]
	v_cvt_pk_bf16_f32 v106, v106, v107
	v_cvt_pk_bf16_f32 v107, v108, v109
	v_cvt_pk_bf16_f32 v108, v110, v111
	v_cvt_pk_bf16_f32 v109, v112, v113
	global_store_dwordx4 v[114:115], v[106:109], off nt
	v_pk_mul_f32 v[100:101], v[146:147], v[100:101] op_sel_hi:[0,1]
	v_pk_mul_f32 v[98:99], v[146:147], v[98:99] op_sel_hi:[0,1]
	v_pk_mul_f32 v[106:107], v[146:147], v[92:93] op_sel_hi:[0,1]
	v_pk_mul_f32 v[92:93], v[146:147], v[90:91] op_sel_hi:[0,1]
	v_cvt_pk_bf16_f32 v90, v98, v99
	v_cvt_pk_bf16_f32 v91, v100, v101
	v_cvt_pk_bf16_f32 v92, v92, v93
	v_cvt_pk_bf16_f32 v93, v106, v107
	global_store_dwordx4 v[114:115], v[90:93], off offset:256 nt
	v_pk_mul_f32 v[96:97], v[146:147], v[96:97] op_sel_hi:[0,1]
	v_pk_mul_f32 v[94:95], v[146:147], v[94:95] op_sel_hi:[0,1]
	v_add_u32_e32 v90, 32, v160
	v_pk_mul_f32 v[92:93], v[146:147], v[104:105] op_sel_hi:[0,1]
	v_mad_i64_i32 v[98:99], s[0:1], v90, s49, v[148:149]
	v_pk_mul_f32 v[90:91], v[146:147], v[102:103] op_sel_hi:[0,1]
	v_cvt_pk_bf16_f32 v90, v90, v91
	v_cvt_pk_bf16_f32 v91, v92, v93
	v_cvt_pk_bf16_f32 v92, v94, v95
	v_cvt_pk_bf16_f32 v93, v96, v97
	global_store_dwordx4 v[98:99], v[90:93], off nt
	v_pk_mul_f32 v[84:85], v[146:147], v[84:85] op_sel_hi:[0,1]
	v_pk_mul_f32 v[82:83], v[146:147], v[82:83] op_sel_hi:[0,1]
	v_pk_mul_f32 v[90:91], v[146:147], v[76:77] op_sel_hi:[0,1]
	v_pk_mul_f32 v[76:77], v[146:147], v[74:75] op_sel_hi:[0,1]
	v_cvt_pk_bf16_f32 v74, v82, v83
	v_cvt_pk_bf16_f32 v75, v84, v85
	v_cvt_pk_bf16_f32 v76, v76, v77
	v_cvt_pk_bf16_f32 v77, v90, v91
	global_store_dwordx4 v[98:99], v[74:77], off offset:256 nt
	v_pk_mul_f32 v[80:81], v[146:147], v[80:81] op_sel_hi:[0,1]
	v_pk_mul_f32 v[78:79], v[146:147], v[78:79] op_sel_hi:[0,1]
	v_add_u32_e32 v74, 48, v160
	v_pk_mul_f32 v[76:77], v[146:147], v[88:89] op_sel_hi:[0,1]
	v_mad_i64_i32 v[82:83], s[0:1], v74, s49, v[148:149]
	v_pk_mul_f32 v[74:75], v[146:147], v[86:87] op_sel_hi:[0,1]
	v_cvt_pk_bf16_f32 v74, v74, v75
	v_cvt_pk_bf16_f32 v75, v76, v77
	v_cvt_pk_bf16_f32 v76, v78, v79
	v_cvt_pk_bf16_f32 v77, v80, v81
	global_store_dwordx4 v[82:83], v[74:77], off nt
	v_pk_mul_f32 v[72:73], v[146:147], v[72:73] op_sel_hi:[0,1]
	v_pk_mul_f32 v[70:71], v[146:147], v[70:71] op_sel_hi:[0,1]
	v_pk_mul_f32 v[74:75], v[146:147], v[68:69] op_sel_hi:[0,1]
	v_pk_mul_f32 v[68:69], v[146:147], v[66:67] op_sel_hi:[0,1]
	v_cvt_pk_bf16_f32 v66, v70, v71
	v_cvt_pk_bf16_f32 v67, v72, v73
	v_cvt_pk_bf16_f32 v68, v68, v69
	v_cvt_pk_bf16_f32 v69, v74, v75
	global_store_dwordx4 v[82:83], v[66:69], off offset:256 nt
	v_pk_mul_f32 v[64:65], v[146:147], v[64:65] op_sel_hi:[0,1]
	v_pk_mul_f32 v[62:63], v[146:147], v[62:63] op_sel_hi:[0,1]
	v_add_u32_e32 v66, 0x80, v160
	v_pk_mul_f32 v[68:69], v[146:147], v[60:61] op_sel_hi:[0,1]
	v_pk_mul_f32 v[60:61], v[146:147], v[58:59] op_sel_hi:[0,1]
	v_mad_i64_i32 v[66:67], s[0:1], v66, s49, v[148:149]
	v_cvt_pk_bf16_f32 v58, v62, v63
	v_cvt_pk_bf16_f32 v59, v64, v65
	v_cvt_pk_bf16_f32 v60, v60, v61
	v_cvt_pk_bf16_f32 v61, v68, v69
	global_store_dwordx4 v[66:67], v[58:61], off nt
	v_pk_mul_f32 v[52:53], v[146:147], v[52:53] op_sel_hi:[0,1]
	v_pk_mul_f32 v[50:51], v[146:147], v[50:51] op_sel_hi:[0,1]
	v_pk_mul_f32 v[58:59], v[146:147], v[44:45] op_sel_hi:[0,1]
	v_pk_mul_f32 v[44:45], v[146:147], v[42:43] op_sel_hi:[0,1]
	v_cvt_pk_bf16_f32 v42, v50, v51
	v_cvt_pk_bf16_f32 v43, v52, v53
	v_cvt_pk_bf16_f32 v44, v44, v45
	v_cvt_pk_bf16_f32 v45, v58, v59
	global_store_dwordx4 v[66:67], v[42:45], off offset:256 nt
	v_pk_mul_f32 v[48:49], v[146:147], v[48:49] op_sel_hi:[0,1]
	v_pk_mul_f32 v[46:47], v[146:147], v[46:47] op_sel_hi:[0,1]
	v_add_u32_e32 v42, 0x90, v160
	v_pk_mul_f32 v[44:45], v[146:147], v[56:57] op_sel_hi:[0,1]
	v_mad_i64_i32 v[50:51], s[0:1], v42, s49, v[148:149]
	v_pk_mul_f32 v[42:43], v[146:147], v[54:55] op_sel_hi:[0,1]
	v_cvt_pk_bf16_f32 v42, v42, v43
	v_cvt_pk_bf16_f32 v43, v44, v45
	v_cvt_pk_bf16_f32 v44, v46, v47
	v_cvt_pk_bf16_f32 v45, v48, v49
	global_store_dwordx4 v[50:51], v[42:45], off nt
	v_pk_mul_f32 v[36:37], v[146:147], v[36:37] op_sel_hi:[0,1]
	v_pk_mul_f32 v[34:35], v[146:147], v[34:35] op_sel_hi:[0,1]
	v_pk_mul_f32 v[42:43], v[146:147], v[28:29] op_sel_hi:[0,1]
	v_pk_mul_f32 v[28:29], v[146:147], v[26:27] op_sel_hi:[0,1]
	v_cvt_pk_bf16_f32 v26, v34, v35
	v_cvt_pk_bf16_f32 v27, v36, v37
	v_cvt_pk_bf16_f32 v28, v28, v29
	v_cvt_pk_bf16_f32 v29, v42, v43
	global_store_dwordx4 v[50:51], v[26:29], off offset:256 nt
	v_pk_mul_f32 v[32:33], v[146:147], v[32:33] op_sel_hi:[0,1]
	v_pk_mul_f32 v[30:31], v[146:147], v[30:31] op_sel_hi:[0,1]
	v_add_u32_e32 v26, 0xa0, v160
	v_pk_mul_f32 v[28:29], v[146:147], v[40:41] op_sel_hi:[0,1]
	v_mad_i64_i32 v[34:35], s[0:1], v26, s49, v[148:149]
	v_pk_mul_f32 v[26:27], v[146:147], v[38:39] op_sel_hi:[0,1]
	v_cvt_pk_bf16_f32 v26, v26, v27
	v_cvt_pk_bf16_f32 v27, v28, v29
	v_cvt_pk_bf16_f32 v28, v30, v31
	v_cvt_pk_bf16_f32 v29, v32, v33
	global_store_dwordx4 v[34:35], v[26:29], off nt
	v_pk_mul_f32 v[20:21], v[146:147], v[20:21] op_sel_hi:[0,1]
	v_pk_mul_f32 v[18:19], v[146:147], v[18:19] op_sel_hi:[0,1]
	v_pk_mul_f32 v[26:27], v[146:147], v[12:13] op_sel_hi:[0,1]
	v_pk_mul_f32 v[12:13], v[146:147], v[10:11] op_sel_hi:[0,1]
	v_cvt_pk_bf16_f32 v10, v18, v19
	v_cvt_pk_bf16_f32 v11, v20, v21
	v_cvt_pk_bf16_f32 v12, v12, v13
	v_cvt_pk_bf16_f32 v13, v26, v27
	global_store_dwordx4 v[34:35], v[10:13], off offset:256 nt
	v_pk_mul_f32 v[16:17], v[146:147], v[16:17] op_sel_hi:[0,1]
	v_pk_mul_f32 v[14:15], v[146:147], v[14:15] op_sel_hi:[0,1]
	v_add_u32_e32 v10, 0xb0, v160
	v_pk_mul_f32 v[12:13], v[146:147], v[24:25] op_sel_hi:[0,1]
	v_mad_i64_i32 v[18:19], s[0:1], v10, s49, v[148:149]
	v_pk_mul_f32 v[10:11], v[146:147], v[22:23] op_sel_hi:[0,1]
	v_cvt_pk_bf16_f32 v10, v10, v11
	v_cvt_pk_bf16_f32 v11, v12, v13
	v_cvt_pk_bf16_f32 v12, v14, v15
	v_cvt_pk_bf16_f32 v13, v16, v17
	global_store_dwordx4 v[18:19], v[10:13], off nt
	v_pk_mul_f32 v[8:9], v[146:147], v[8:9] op_sel_hi:[0,1]
	v_pk_mul_f32 v[6:7], v[146:147], v[6:7] op_sel_hi:[0,1]
	v_pk_mul_f32 v[10:11], v[146:147], v[4:5] op_sel_hi:[0,1]
	v_pk_mul_f32 v[4:5], v[146:147], v[2:3] op_sel_hi:[0,1]
	v_cvt_pk_bf16_f32 v2, v6, v7
	v_cvt_pk_bf16_f32 v3, v8, v9
	v_cvt_pk_bf16_f32 v4, v4, v5
	v_cvt_pk_bf16_f32 v5, v10, v11
	global_store_dwordx4 v[18:19], v[2:5], off offset:256 nt
	s_branch .LBB0_891

.LBB0_1513:
	ds_read_b128 v[152:155], v149
	ds_read_b128 v[156:159], v149 offset:1024
	ds_read_b128 v[160:163], v149 offset:2048
	ds_read_b128 v[164:167], v149 offset:3072
	s_add_u32 s0, s26, 0xfffc0080
	s_addc_u32 s1, s27, -1
	s_cmp_eq_u32 s49, 12
	s_cselect_b32 s31, s21, s1
	s_cselect_b32 s30, s45, s0
	s_cselect_b32 s29, s19, s48
	s_cselect_b32 s28, s46, s47
	v_lshl_add_u64 v[200:201], s[26:27], 0, v[140:141]
	s_add_i32 m0, s10, 0xc000
	ds_read_b128 v[168:171], v150
	ds_read_b128 v[172:175], v150 offset:1024
	ds_read_b128 v[176:179], v150 offset:2048
	ds_read_b128 v[180:183], v150 offset:3072
	ds_read_b128 v[184:187], v150 offset:4096
	ds_read_b128 v[188:191], v150 offset:5120
	ds_read_b128 v[192:195], v150 offset:6144
	ds_read_b128 v[196:199], v150 offset:7168
	global_load_lds_dwordx4 v[200:201], off
	v_lshl_add_u64 v[200:201], s[26:27], 0, v[138:139]
	s_add_i32 m0, s10, 0xe000
	s_nop 0
	global_load_lds_dwordx4 v[200:201], off
	s_waitcnt lgkmcnt(8)
	s_waitcnt vmcnt(10)
	s_barrier
	s_waitcnt lgkmcnt(0)
	s_waitcnt lgkmcnt(0)
	v_mfma_f32_16x16x32_bf16 v[126:129], v[152:155], v[168:171], v[126:129]
	v_mfma_f32_16x16x32_bf16 v[122:125], v[160:163], v[168:171], v[122:125]
	v_mfma_f32_16x16x32_bf16 v[118:121], v[152:155], v[176:179], v[118:121]
	v_mfma_f32_16x16x32_bf16 v[110:113], v[160:163], v[176:179], v[110:113]
	v_mfma_f32_16x16x32_bf16 v[102:105], v[152:155], v[184:187], v[102:105]
	v_mfma_f32_16x16x32_bf16 v[94:97], v[160:163], v[184:187], v[94:97]
	v_mfma_f32_16x16x32_bf16 v[86:89], v[152:155], v[192:195], v[86:89]
	v_mfma_f32_16x16x32_bf16 v[78:81], v[160:163], v[192:195], v[78:81]
	v_mfma_f32_16x16x32_bf16 v[126:129], v[156:159], v[172:175], v[126:129]
	v_mfma_f32_16x16x32_bf16 v[122:125], v[164:167], v[172:175], v[122:125]
	v_mfma_f32_16x16x32_bf16 v[118:121], v[156:159], v[180:183], v[118:121]
	v_mfma_f32_16x16x32_bf16 v[110:113], v[164:167], v[180:183], v[110:113]
	v_mfma_f32_16x16x32_bf16 v[102:105], v[156:159], v[188:191], v[102:105]
	v_mfma_f32_16x16x32_bf16 v[94:97], v[164:167], v[188:191], v[94:97]
	v_mfma_f32_16x16x32_bf16 v[86:89], v[156:159], v[196:199], v[86:89]
	v_mfma_f32_16x16x32_bf16 v[78:81], v[164:167], v[196:199], v[78:81]
	s_barrier
	s_add_i32 s0, s42, s9
	v_lshl_add_u64 v[216:217], s[28:29], 0, v[134:135]
	s_mov_b32 m0, s0
	ds_read_b128 v[200:203], v151
	ds_read_b128 v[204:207], v151 offset:1024
	ds_read_b128 v[208:211], v151 offset:2048
	ds_read_b128 v[212:215], v151 offset:3072
	global_load_lds_dwordx4 v[216:217], off
	v_lshl_add_u64 v[218:219], s[28:29], 0, v[130:131]
	s_add_i32 m0, s0, 0x2000
	s_nop 0
	global_load_lds_dwordx4 v[218:219], off
	s_waitcnt vmcnt(10)
	s_barrier
	s_waitcnt lgkmcnt(0)
	s_waitcnt lgkmcnt(0)
	v_mfma_f32_16x16x32_bf16 v[114:117], v[200:203], v[168:171], v[114:117]
	v_mfma_f32_16x16x32_bf16 v[106:109], v[208:211], v[168:171], v[106:109]
	v_mfma_f32_16x16x32_bf16 v[98:101], v[200:203], v[176:179], v[98:101]
	v_mfma_f32_16x16x32_bf16 v[90:93], v[208:211], v[176:179], v[90:93]
	v_mfma_f32_16x16x32_bf16 v[82:85], v[200:203], v[184:187], v[82:85]
	v_mfma_f32_16x16x32_bf16 v[74:77], v[208:211], v[184:187], v[74:77]
	v_mfma_f32_16x16x32_bf16 v[70:73], v[200:203], v[192:195], v[70:73]
	v_mfma_f32_16x16x32_bf16 v[66:69], v[208:211], v[192:195], v[66:69]
	v_mfma_f32_16x16x32_bf16 v[114:117], v[204:207], v[172:175], v[114:117]
	v_mfma_f32_16x16x32_bf16 v[106:109], v[212:215], v[172:175], v[106:109]
	v_mfma_f32_16x16x32_bf16 v[98:101], v[204:207], v[180:183], v[98:101]
	v_mfma_f32_16x16x32_bf16 v[90:93], v[212:215], v[180:183], v[90:93]
	v_mfma_f32_16x16x32_bf16 v[82:85], v[204:207], v[188:191], v[82:85]
	v_mfma_f32_16x16x32_bf16 v[74:77], v[212:215], v[188:191], v[74:77]
	v_mfma_f32_16x16x32_bf16 v[70:73], v[204:207], v[196:199], v[70:73]
	v_mfma_f32_16x16x32_bf16 v[66:69], v[212:215], v[196:199], v[66:69]
	s_mov_b32 m0, s10
	v_lshl_add_u64 v[220:221], s[30:31], 0, v[136:137]
	s_barrier
	ds_read_b128 v[168:171], v150 offset:16384
	ds_read_b128 v[172:175], v150 offset:17408
	ds_read_b128 v[176:179], v150 offset:18432
	ds_read_b128 v[180:183], v150 offset:19456
	ds_read_b128 v[184:187], v150 offset:20480
	ds_read_b128 v[188:191], v150 offset:21504
	ds_read_b128 v[192:195], v150 offset:22528
	ds_read_b128 v[196:199], v150 offset:23552
	global_load_lds_dwordx4 v[220:221], off
	v_lshl_add_u64 v[222:223], s[30:31], 0, v[132:133]
	s_mov_b32 m0, s11
	s_nop 0
	global_load_lds_dwordx4 v[222:223], off
	s_waitcnt vmcnt(10)
	s_barrier
	s_waitcnt lgkmcnt(0)
	s_waitcnt lgkmcnt(0)
	v_mfma_f32_16x16x32_bf16 v[62:65], v[152:155], v[168:171], v[62:65]
	v_mfma_f32_16x16x32_bf16 v[58:61], v[160:163], v[168:171], v[58:61]
	v_mfma_f32_16x16x32_bf16 v[54:57], v[152:155], v[176:179], v[54:57]
	v_mfma_f32_16x16x32_bf16 v[50:53], v[160:163], v[176:179], v[50:53]
	v_mfma_f32_16x16x32_bf16 v[38:41], v[152:155], v[184:187], v[38:41]
	v_mfma_f32_16x16x32_bf16 v[34:37], v[160:163], v[184:187], v[34:37]
	v_mfma_f32_16x16x32_bf16 v[22:25], v[152:155], v[192:195], v[22:25]
	v_mfma_f32_16x16x32_bf16 v[18:21], v[160:163], v[192:195], v[18:21]
	v_mfma_f32_16x16x32_bf16 v[62:65], v[156:159], v[172:175], v[62:65]
	v_mfma_f32_16x16x32_bf16 v[58:61], v[164:167], v[172:175], v[58:61]
	v_mfma_f32_16x16x32_bf16 v[54:57], v[156:159], v[180:183], v[54:57]
	v_mfma_f32_16x16x32_bf16 v[50:53], v[164:167], v[180:183], v[50:53]
	v_mfma_f32_16x16x32_bf16 v[38:41], v[156:159], v[188:191], v[38:41]
	v_mfma_f32_16x16x32_bf16 v[34:37], v[164:167], v[188:191], v[34:37]
	v_mfma_f32_16x16x32_bf16 v[22:25], v[156:159], v[196:199], v[22:25]
	v_mfma_f32_16x16x32_bf16 v[18:21], v[164:167], v[196:199], v[18:21]
	s_barrier
	s_add_u32 s0, s28, 0x40000
	s_addc_u32 s1, s29, 0
	s_add_i32 s50, s43, s9
	v_lshl_add_u64 v[152:153], s[0:1], 0, v[134:135]
	s_mov_b32 m0, s50
	s_nop 0
	global_load_lds_dwordx4 v[152:153], off
	v_lshl_add_u64 v[152:153], s[0:1], 0, v[130:131]
	s_add_i32 m0, s50, 0x2000
	s_nop 0
	global_load_lds_dwordx4 v[152:153], off
	s_waitcnt vmcnt(10)
	s_barrier
	v_mfma_f32_16x16x32_bf16 v[46:49], v[200:203], v[168:171], v[46:49]
	v_mfma_f32_16x16x32_bf16 v[42:45], v[208:211], v[168:171], v[42:45]
	v_mfma_f32_16x16x32_bf16 v[30:33], v[200:203], v[176:179], v[30:33]
	v_mfma_f32_16x16x32_bf16 v[26:29], v[208:211], v[176:179], v[26:29]
	v_mfma_f32_16x16x32_bf16 v[14:17], v[200:203], v[184:187], v[14:17]
	v_mfma_f32_16x16x32_bf16 v[10:13], v[208:211], v[184:187], v[10:13]
	v_mfma_f32_16x16x32_bf16 v[6:9], v[200:203], v[192:195], v[6:9]
	v_mfma_f32_16x16x32_bf16 v[2:5], v[208:211], v[192:195], v[2:5]
	v_mfma_f32_16x16x32_bf16 v[46:49], v[204:207], v[172:175], v[46:49]
	v_mfma_f32_16x16x32_bf16 v[42:45], v[212:215], v[172:175], v[42:45]
	v_mfma_f32_16x16x32_bf16 v[30:33], v[204:207], v[180:183], v[30:33]
	v_mfma_f32_16x16x32_bf16 v[26:29], v[212:215], v[180:183], v[26:29]
	v_mfma_f32_16x16x32_bf16 v[14:17], v[204:207], v[188:191], v[14:17]
	v_mfma_f32_16x16x32_bf16 v[10:13], v[212:215], v[188:191], v[10:13]
	v_mfma_f32_16x16x32_bf16 v[6:9], v[204:207], v[196:199], v[6:9]
	v_mfma_f32_16x16x32_bf16 v[2:5], v[212:215], v[196:199], v[2:5]
	s_add_i32 s50, 0, 0x18000
	v_add_u32_e32 v164, s50, v148
	s_barrier
	ds_read_b128 v[152:155], v164
	ds_read_b128 v[156:159], v164 offset:1024
	ds_read_b128 v[160:163], v164 offset:2048
	ds_read_b128 v[164:167], v164 offset:3072
	s_add_u32 s0, s30, 0x40000
	s_addc_u32 s1, s31, 0
	s_mov_b32 m0, s17
	v_lshl_add_u64 v[200:201], s[0:1], 0, v[136:137]
	ds_read_b128 v[168:171], v150 offset:32768
	ds_read_b128 v[172:175], v150 offset:33792
	ds_read_b128 v[176:179], v150 offset:34816
	ds_read_b128 v[180:183], v150 offset:35840
	ds_read_b128 v[184:187], v150 offset:36864
	ds_read_b128 v[188:191], v150 offset:37888
	ds_read_b128 v[192:195], v150 offset:38912
	ds_read_b128 v[196:199], v150 offset:39936
	global_load_lds_dwordx4 v[200:201], off
	v_lshl_add_u64 v[200:201], s[0:1], 0, v[132:133]
	s_mov_b32 m0, s34
	s_nop 0
	global_load_lds_dwordx4 v[200:201], off
	s_waitcnt lgkmcnt(8)
	s_waitcnt vmcnt(10)
	s_barrier
	s_waitcnt lgkmcnt(0)
	s_waitcnt lgkmcnt(0)
	v_mfma_f32_16x16x32_bf16 v[126:129], v[152:155], v[168:171], v[126:129]
	v_mfma_f32_16x16x32_bf16 v[122:125], v[160:163], v[168:171], v[122:125]
	v_mfma_f32_16x16x32_bf16 v[118:121], v[152:155], v[176:179], v[118:121]
	v_mfma_f32_16x16x32_bf16 v[110:113], v[160:163], v[176:179], v[110:113]
	v_mfma_f32_16x16x32_bf16 v[102:105], v[152:155], v[184:187], v[102:105]
	v_mfma_f32_16x16x32_bf16 v[94:97], v[160:163], v[184:187], v[94:97]
	v_mfma_f32_16x16x32_bf16 v[86:89], v[152:155], v[192:195], v[86:89]
	v_mfma_f32_16x16x32_bf16 v[78:81], v[160:163], v[192:195], v[78:81]
	v_mfma_f32_16x16x32_bf16 v[126:129], v[156:159], v[172:175], v[126:129]
	v_mfma_f32_16x16x32_bf16 v[122:125], v[164:167], v[172:175], v[122:125]
	v_mfma_f32_16x16x32_bf16 v[118:121], v[156:159], v[180:183], v[118:121]
	v_mfma_f32_16x16x32_bf16 v[110:113], v[164:167], v[180:183], v[110:113]
	v_mfma_f32_16x16x32_bf16 v[102:105], v[156:159], v[188:191], v[102:105]
	v_mfma_f32_16x16x32_bf16 v[94:97], v[164:167], v[188:191], v[94:97]
	v_mfma_f32_16x16x32_bf16 v[86:89], v[156:159], v[196:199], v[86:89]
	v_mfma_f32_16x16x32_bf16 v[78:81], v[164:167], v[196:199], v[78:81]
	s_barrier
	s_add_i32 s30, 0, 0x1c000
	s_add_i32 s0, s50, s9
	v_add_u32_e32 v212, s30, v148
	v_lshl_add_u64 v[216:217], v[216:217], 0, s[14:15]
	s_mov_b32 m0, s0
	ds_read_b128 v[200:203], v212
	ds_read_b128 v[204:207], v212 offset:1024
	ds_read_b128 v[208:211], v212 offset:2048
	ds_read_b128 v[212:215], v212 offset:3072
	global_load_lds_dwordx4 v[216:217], off
	v_lshl_add_u64 v[216:217], v[218:219], 0, s[14:15]
	s_add_i32 m0, s0, 0x2000
	s_nop 0
	global_load_lds_dwordx4 v[216:217], off
	s_waitcnt vmcnt(10)
	s_barrier
	s_waitcnt lgkmcnt(0)
	s_waitcnt lgkmcnt(0)
	v_mfma_f32_16x16x32_bf16 v[114:117], v[200:203], v[168:171], v[114:117]
	v_mfma_f32_16x16x32_bf16 v[106:109], v[208:211], v[168:171], v[106:109]
	v_mfma_f32_16x16x32_bf16 v[98:101], v[200:203], v[176:179], v[98:101]
	v_mfma_f32_16x16x32_bf16 v[90:93], v[208:211], v[176:179], v[90:93]
	v_mfma_f32_16x16x32_bf16 v[82:85], v[200:203], v[184:187], v[82:85]
	v_mfma_f32_16x16x32_bf16 v[74:77], v[208:211], v[184:187], v[74:77]
	v_mfma_f32_16x16x32_bf16 v[70:73], v[200:203], v[192:195], v[70:73]
	v_mfma_f32_16x16x32_bf16 v[66:69], v[208:211], v[192:195], v[66:69]
	v_mfma_f32_16x16x32_bf16 v[114:117], v[204:207], v[172:175], v[114:117]
	v_mfma_f32_16x16x32_bf16 v[106:109], v[212:215], v[172:175], v[106:109]
	v_mfma_f32_16x16x32_bf16 v[98:101], v[204:207], v[180:183], v[98:101]
	v_mfma_f32_16x16x32_bf16 v[90:93], v[212:215], v[180:183], v[90:93]
	v_mfma_f32_16x16x32_bf16 v[82:85], v[204:207], v[188:191], v[82:85]
	v_mfma_f32_16x16x32_bf16 v[74:77], v[212:215], v[188:191], v[74:77]
	v_mfma_f32_16x16x32_bf16 v[70:73], v[204:207], v[196:199], v[70:73]
	v_mfma_f32_16x16x32_bf16 v[66:69], v[212:215], v[196:199], v[66:69]
	s_mov_b32 m0, s40
	v_lshl_add_u64 v[216:217], v[220:221], 0, s[14:15]
	s_barrier
	ds_read_b128 v[168:171], v150 offset:49152
	ds_read_b128 v[172:175], v150 offset:50176
	ds_read_b128 v[176:179], v150 offset:51200
	ds_read_b128 v[180:183], v150 offset:52224
	ds_read_b128 v[184:187], v150 offset:53248
	ds_read_b128 v[188:191], v150 offset:54272
	ds_read_b128 v[192:195], v150 offset:55296
	ds_read_b128 v[196:199], v150 offset:56320
	global_load_lds_dwordx4 v[216:217], off
	v_lshl_add_u64 v[216:217], v[222:223], 0, s[14:15]
	s_mov_b32 m0, s41
	s_nop 0
	global_load_lds_dwordx4 v[216:217], off
	s_waitcnt vmcnt(10)
	s_barrier
	s_waitcnt lgkmcnt(0)
	s_waitcnt lgkmcnt(0)
	v_mfma_f32_16x16x32_bf16 v[62:65], v[152:155], v[168:171], v[62:65]
	v_mfma_f32_16x16x32_bf16 v[58:61], v[160:163], v[168:171], v[58:61]
	v_mfma_f32_16x16x32_bf16 v[54:57], v[152:155], v[176:179], v[54:57]
	v_mfma_f32_16x16x32_bf16 v[50:53], v[160:163], v[176:179], v[50:53]
	v_mfma_f32_16x16x32_bf16 v[38:41], v[152:155], v[184:187], v[38:41]
	v_mfma_f32_16x16x32_bf16 v[34:37], v[160:163], v[184:187], v[34:37]
	v_mfma_f32_16x16x32_bf16 v[22:25], v[152:155], v[192:195], v[22:25]
	v_mfma_f32_16x16x32_bf16 v[18:21], v[160:163], v[192:195], v[18:21]
	v_mfma_f32_16x16x32_bf16 v[62:65], v[156:159], v[172:175], v[62:65]
	v_mfma_f32_16x16x32_bf16 v[58:61], v[164:167], v[172:175], v[58:61]
	v_mfma_f32_16x16x32_bf16 v[54:57], v[156:159], v[180:183], v[54:57]
	v_mfma_f32_16x16x32_bf16 v[50:53], v[164:167], v[180:183], v[50:53]
	v_mfma_f32_16x16x32_bf16 v[38:41], v[156:159], v[188:191], v[38:41]
	v_mfma_f32_16x16x32_bf16 v[34:37], v[164:167], v[188:191], v[34:37]
	v_mfma_f32_16x16x32_bf16 v[22:25], v[156:159], v[196:199], v[22:25]
	v_mfma_f32_16x16x32_bf16 v[18:21], v[164:167], v[196:199], v[18:21]
	s_barrier
	s_add_u32 s0, s28, 0x40080
	s_addc_u32 s1, s29, 0
	s_add_i32 s28, s30, s9
	v_lshl_add_u64 v[152:153], s[0:1], 0, v[134:135]
	s_mov_b32 m0, s28
	s_nop 0
	global_load_lds_dwordx4 v[152:153], off
	v_lshl_add_u64 v[152:153], s[0:1], 0, v[130:131]
	s_add_i32 m0, s28, 0x2000
	s_nop 0
	global_load_lds_dwordx4 v[152:153], off
	s_waitcnt vmcnt(10)
	s_barrier
	v_mfma_f32_16x16x32_bf16 v[46:49], v[200:203], v[168:171], v[46:49]
	v_mfma_f32_16x16x32_bf16 v[42:45], v[208:211], v[168:171], v[42:45]
	v_mfma_f32_16x16x32_bf16 v[30:33], v[200:203], v[176:179], v[30:33]
	v_mfma_f32_16x16x32_bf16 v[26:29], v[208:211], v[176:179], v[26:29]
	v_mfma_f32_16x16x32_bf16 v[14:17], v[200:203], v[184:187], v[14:17]
	v_mfma_f32_16x16x32_bf16 v[10:13], v[208:211], v[184:187], v[10:13]
	v_mfma_f32_16x16x32_bf16 v[6:9], v[200:203], v[192:195], v[6:9]
	v_mfma_f32_16x16x32_bf16 v[2:5], v[208:211], v[192:195], v[2:5]
	v_mfma_f32_16x16x32_bf16 v[46:49], v[204:207], v[172:175], v[46:49]
	v_mfma_f32_16x16x32_bf16 v[42:45], v[212:215], v[172:175], v[42:45]
	v_mfma_f32_16x16x32_bf16 v[30:33], v[204:207], v[180:183], v[30:33]
	v_mfma_f32_16x16x32_bf16 v[26:29], v[212:215], v[180:183], v[26:29]
	v_mfma_f32_16x16x32_bf16 v[14:17], v[204:207], v[188:191], v[14:17]
	v_mfma_f32_16x16x32_bf16 v[10:13], v[212:215], v[188:191], v[10:13]
	v_mfma_f32_16x16x32_bf16 v[6:9], v[204:207], v[196:199], v[6:9]
	v_mfma_f32_16x16x32_bf16 v[2:5], v[212:215], v[196:199], v[2:5]
	s_add_i32 s49, s49, 2
	s_add_u32 s47, s47, 0x100
	s_addc_u32 s48, s48, 0
	s_add_u32 s26, s26, 0x100
	s_addc_u32 s27, s27, 0
	s_cmp_gt_u32 s49, 13
	s_barrier
	s_cbranch_scc0 .LBB0_1513
	v_mov_b32_e32 v152, v146
	v_mov_b32_e32 v153, v147
	s_cmp_gt_i32 s44, 7
	s_cbranch_scc1 .LBB0_1505
	s_ashr_i32 s0, s44, 31
	s_lshr_b32 s0, s0, 30
	s_add_i32 s0, s44, s0
	s_ashr_i32 s0, s0, 2
	s_ashr_i32 s1, s0, 31
	s_lshl_b32 s19, s44, 8
	s_lshl_b64 s[26:27], s[0:1], 27
	s_add_u32 s26, s36, s26
	s_addc_u32 s27, s37, s27
	s_or_b32 s1, s19, s39
	s_lshl_b32 s0, s0, 10
	s_sub_i32 s0, s1, s0
	v_lshl_add_u32 v154, v153, 3, s0
	s_lshl_b32 s0, s16, 8
	s_add_i32 s0, s0, s38
	v_add_u32_e32 v156, s0, v152
	v_mov_b32_e32 v152, v156
	v_ashrrev_i32_e32 v155, 31, v154
	v_lshl_add_u64 v[154:155], v[154:155], 1, s[26:27]
	v_ashrrev_i32_e32 v153, 31, v152
	v_lshlrev_b64 v[152:153], 11, v[152:153]
	v_lshl_add_u64 v[152:153], v[154:155], 0, v[152:153]
	v_cvt_pk_bf16_f32 v126, v126, v127
	v_cvt_pk_bf16_f32 v127, v128, v129
	v_cvt_pk_bf16_f32 v128, v122, v123
	v_cvt_pk_bf16_f32 v129, v124, v125
	v_cvt_pk_bf16_f32 v114, v114, v115
	v_cvt_pk_bf16_f32 v115, v116, v117
	v_cvt_pk_bf16_f32 v116, v106, v107
	v_cvt_pk_bf16_f32 v117, v108, v109
	v_add_u32_e32 v106, 16, v156
	global_store_dwordx4 v[152:153], v[126:129], off nt
	global_store_dwordx4 v[152:153], v[114:117], off offset:256 nt
	v_cvt_pk_bf16_f32 v108, v110, v111
	v_ashrrev_i32_e32 v107, 31, v106
	v_lshlrev_b64 v[106:107], 11, v[106:107]
	v_lshl_add_u64 v[114:115], v[154:155], 0, v[106:107]
	v_cvt_pk_bf16_f32 v106, v118, v119
	v_cvt_pk_bf16_f32 v107, v120, v121
	v_cvt_pk_bf16_f32 v109, v112, v113
	v_cvt_pk_bf16_f32 v98, v98, v99
	v_cvt_pk_bf16_f32 v99, v100, v101
	v_cvt_pk_bf16_f32 v100, v90, v91
	v_cvt_pk_bf16_f32 v101, v92, v93
	v_add_u32_e32 v90, 32, v156
	global_store_dwordx4 v[114:115], v[106:109], off nt
	global_store_dwordx4 v[114:115], v[98:101], off offset:256 nt
	v_cvt_pk_bf16_f32 v92, v94, v95
	v_ashrrev_i32_e32 v91, 31, v90
	v_lshlrev_b64 v[90:91], 11, v[90:91]
	v_lshl_add_u64 v[98:99], v[154:155], 0, v[90:91]
	v_cvt_pk_bf16_f32 v90, v102, v103
	v_cvt_pk_bf16_f32 v91, v104, v105
	v_cvt_pk_bf16_f32 v93, v96, v97
	v_cvt_pk_bf16_f32 v82, v82, v83
	v_cvt_pk_bf16_f32 v83, v84, v85
	v_cvt_pk_bf16_f32 v84, v74, v75
	v_cvt_pk_bf16_f32 v85, v76, v77
	v_add_u32_e32 v74, 48, v156
	global_store_dwordx4 v[98:99], v[90:93], off nt
	global_store_dwordx4 v[98:99], v[82:85], off offset:256 nt
	v_cvt_pk_bf16_f32 v76, v78, v79
	v_ashrrev_i32_e32 v75, 31, v74
	v_lshlrev_b64 v[74:75], 11, v[74:75]
	v_lshl_add_u64 v[82:83], v[154:155], 0, v[74:75]
	v_cvt_pk_bf16_f32 v74, v86, v87
	v_cvt_pk_bf16_f32 v75, v88, v89
	v_cvt_pk_bf16_f32 v77, v80, v81
	v_cvt_pk_bf16_f32 v70, v70, v71
	v_cvt_pk_bf16_f32 v71, v72, v73
	v_cvt_pk_bf16_f32 v72, v66, v67
	v_cvt_pk_bf16_f32 v73, v68, v69
	v_add_u32_e32 v66, 0x80, v156
	global_store_dwordx4 v[82:83], v[74:77], off nt
	global_store_dwordx4 v[82:83], v[70:73], off offset:256 nt
	v_cvt_pk_bf16_f32 v62, v62, v63
	v_ashrrev_i32_e32 v67, 31, v66
	v_lshlrev_b64 v[66:67], 11, v[66:67]
	v_lshl_add_u64 v[66:67], v[154:155], 0, v[66:67]
	v_cvt_pk_bf16_f32 v63, v64, v65
	v_cvt_pk_bf16_f32 v64, v58, v59
	v_cvt_pk_bf16_f32 v65, v60, v61
	v_cvt_pk_bf16_f32 v46, v46, v47
	v_cvt_pk_bf16_f32 v47, v48, v49
	v_cvt_pk_bf16_f32 v48, v42, v43
	v_cvt_pk_bf16_f32 v49, v44, v45
	v_add_u32_e32 v42, 0x90, v156
	global_store_dwordx4 v[66:67], v[62:65], off nt
	global_store_dwordx4 v[66:67], v[46:49], off offset:256 nt
	v_cvt_pk_bf16_f32 v44, v50, v51
	v_ashrrev_i32_e32 v43, 31, v42
	v_lshlrev_b64 v[42:43], 11, v[42:43]
	v_lshl_add_u64 v[46:47], v[154:155], 0, v[42:43]
	v_cvt_pk_bf16_f32 v42, v54, v55
	v_cvt_pk_bf16_f32 v43, v56, v57
	v_cvt_pk_bf16_f32 v45, v52, v53
	v_cvt_pk_bf16_f32 v30, v30, v31
	v_cvt_pk_bf16_f32 v31, v32, v33
	v_cvt_pk_bf16_f32 v32, v26, v27
	v_cvt_pk_bf16_f32 v33, v28, v29
	v_add_u32_e32 v26, 0xa0, v156
	global_store_dwordx4 v[46:47], v[42:45], off nt
	global_store_dwordx4 v[46:47], v[30:33], off offset:256 nt
	v_cvt_pk_bf16_f32 v28, v34, v35
	v_ashrrev_i32_e32 v27, 31, v26
	v_lshlrev_b64 v[26:27], 11, v[26:27]
	v_lshl_add_u64 v[30:31], v[154:155], 0, v[26:27]
	v_cvt_pk_bf16_f32 v26, v38, v39
	v_cvt_pk_bf16_f32 v27, v40, v41
	v_cvt_pk_bf16_f32 v29, v36, v37
	v_cvt_pk_bf16_f32 v14, v14, v15
	v_cvt_pk_bf16_f32 v15, v16, v17
	v_cvt_pk_bf16_f32 v16, v10, v11
	v_cvt_pk_bf16_f32 v17, v12, v13
	v_add_u32_e32 v10, 0xb0, v156
	global_store_dwordx4 v[30:31], v[26:29], off nt
	global_store_dwordx4 v[30:31], v[14:17], off offset:256 nt
	v_cvt_pk_bf16_f32 v12, v18, v19
	v_ashrrev_i32_e32 v11, 31, v10
	v_lshlrev_b64 v[10:11], 11, v[10:11]
	v_lshl_add_u64 v[14:15], v[154:155], 0, v[10:11]
	v_cvt_pk_bf16_f32 v10, v22, v23
	v_cvt_pk_bf16_f32 v11, v24, v25
	v_cvt_pk_bf16_f32 v13, v20, v21
	v_cvt_pk_bf16_f32 v6, v6, v7
	v_cvt_pk_bf16_f32 v7, v8, v9
	v_cvt_pk_bf16_f32 v8, v2, v3
	v_cvt_pk_bf16_f32 v9, v4, v5
	global_store_dwordx4 v[14:15], v[10:13], off nt
	global_store_dwordx4 v[14:15], v[6:9], off offset:256 nt
	s_branch .LBB0_1505
